# gate/up per-unit scheduler decode: the division by the row-group size (constant 8 for this shape) strength-reduced to a shift, removing the v_rcp/readfirstlane round trip and 26 scalar ops per unit; o
# speedup vs baseline: 1.0044x; 1.0044x over previous
.LBB0_1057:
	s_add_i32 s65, s65, 1
	s_mul_i32 s4, s65, s39
	s_mul_hi_u32 s5, s65, s36
	s_add_i32 s5, s5, s4
	s_mul_i32 s4, s65, s36
	s_add_u32 s20, s4, s37
	s_addc_u32 s21, s5, s66
	v_mov_b64_e32 v[2:3], 0x580
	v_cmp_lt_i64_e64 s[4:5], s[20:21], v[2:3]
	v_mov_b64_e32 v[2:3], 0x57f
	v_cmp_gt_i64_e32 vcc, s[20:21], v[2:3]
	s_cbranch_vccnz .LBB0_1059
	s_ashr_i32 s16, s20, 31
	s_lshr_b32 s16, s16, 29
	s_add_i32 s16, s20, s16
	s_ashr_i32 s17, s16, 3
	s_and_b32 s16, s16, -8
	s_sub_i32 s16, s20, s16
	s_cmp_lt_i32 s16, 0
	s_cselect_b32 s18, s3, 0xb0
	s_mul_i32 s16, s16, s18
	s_add_i32 s16, s16, s17
	s_mul_hi_i32 s17, s16, 0x2e8ba2e9
	s_lshr_b32 s18, s17, 31
	s_ashr_i32 s17, s17, 6
	s_add_i32 s17, s17, s18
	s_lshl_b32 s18, s17, 3
	s_sub_i32 s19, 32, s18
	s_min_i32 s19, s19, 8
	s_mulk_i32 s17, 0x160
	s_sub_i32 s17, s16, s17
	s_ashr_i32 s16, s17, 3
	s_mul_i32 s19, s16, s19
	s_sub_i32 s17, s17, s19
	s_add_i32 s18, s18, s17
